# G3: the item's q/k row loads (both 32-row halves) also requested at item start
# baseline (speedup 1.0000x reference)
; __device__ __forceinline__ unsigned cvt_pk_bf16(float lo, float hi) { unsigned r; asm volatile("v_cvt_pk_bf16_f32 %0, %1, %2" : "=v"(r) : "v"(lo), "v"(hi)); return r; }
; __device__ __forceinline__ float bf_lo(unsigned w) { return __uint_as_float(w << 16); }
; __device__ __forceinline__ float bf_hi(unsigned w) { return __uint_as_float(w & 0xffff0000u); }
; __device__ __forceinline__ void gla_g3(const Params& P, unsigned char* lds) {
;     ...
;         for (int p = 0; p < 2; ++p) { const int idx = tid + p * NT, t = idx >> 4, c8 = (idx & 15) * 8; u32x4 qo = (u32x4){0u, 0u, 0u, 0u}, ko = (u32x4){0u, 0u, 0u, 0u};
;             const int tcl = t < I.L ? t : I.L - 1; const u32x4 qw = *(const u32x4*)(qg + (size_t)(I.row0 + tcl) * KEYD + I.h * DK + c8), kw = *(const u32x4*)(kg + (size_t)(I.row0 + tcl) * KEYD + I.h * DK + c8);
;             if (t < I.L) {
;                 const f32x4 b0 = *(const f32x4*)(bsh + t * 128 + c8), b1 = *(const f32x4*)(bsh + t * 128 + c8 + 4);
;                 float e[8], ei[8];
; #pragma unroll
;                 for (int j = 0; j < 4; ++j) { e[j] = __expf(b0[j]); e[4 + j] = __expf(b1[j]); ei[j] = __expf(-b0[j]); ei[4 + j] = __expf(-b1[j]); }
;                 qo.x = cvt_pk_bf16(bf_lo(qw.x) * e[0], bf_hi(qw.x) * e[1]); qo.y = cvt_pk_bf16(bf_lo(qw.y) * e[2], bf_hi(qw.y) * e[3]); qo.z = cvt_pk_bf16(bf_lo(qw.z) * e[4], bf_hi(qw.z) * e[5]); qo.w = cvt_pk_bf16(bf_lo(qw.w) * e[6], bf_hi(qw.w) * e[7]);
;                 ko.x = cvt_pk_bf16(bf_lo(kw.x) * ei[0], bf_hi(kw.x) * ei[1]); ko.y = cvt_pk_bf16(bf_lo(kw.y) * ei[2], bf_hi(kw.y) * ei[3]); ko.z = cvt_pk_bf16(bf_lo(kw.z) * ei[4], bf_hi(kw.z) * ei[5]); ko.w = cvt_pk_bf16(bf_lo(kw.w) * ei[6], bf_hi(kw.w) * ei[7]); }
;             *(u32x4*)(qd + t * 136 + c8) = qo; *(u32x4*)(kin + t * 136 + c8) = ko; }
.Lg3_tail:
	s_add_i32 s64, s95, -1
	v_lshl_add_u64 v[44:45], v[66:67], 0, s[46:47]
	v_lshl_add_u64 v[42:43], v[68:69], 0, s[46:47]
	v_cmp_gt_u32_e32 vcc, s95, v102
	v_mov_b32_e32 v32, 0
	v_mov_b32_e32 v34, 0
	v_mov_b32_e32 v35, 0
	v_mov_b32_e32 v36, 0
	v_mov_b32_e32 v37, 0
	v_mov_b32_e32 v38, 0
	v_mov_b32_e32 v39, 0
	v_mov_b32_e32 v40, 0
	v_mov_b32_e32 v41, 0
	s_waitcnt lgkmcnt(0)
	s_barrier
	s_and_saveexec_b64 s[38:39], vcc
	s_cbranch_execz .LBB0_2152
	v_min_u32_e32 v33, s64, v102
	v_add_u32_e32 v34, s60, v33
	v_ashrrev_i32_e32 v35, 31, v34
	v_lshlrev_b64 v[38:39], 10, v[34:35]
	v_lshl_add_u64 v[34:35], v[44:45], 0, v[38:39]
	s_waitcnt vmcnt(4)
	v_mov_b32_e32 v34, v228
	v_mov_b32_e32 v35, v229
	v_mov_b32_e32 v36, v230
	v_mov_b32_e32 v37, v231
	v_lshl_add_u64 v[38:39], v[42:43], 0, v[38:39]
	v_mov_b32_e32 v38, v232
	v_mov_b32_e32 v39, v233
	v_mov_b32_e32 v40, v234
	v_mov_b32_e32 v41, v235
	ds_read_b128 v[46:49], v163 offset:4096
	ds_read_b128 v[50:53], v163 offset:4112
	s_waitcnt lgkmcnt(1)
	v_mul_f32_e32 v55, 0x3fb8aa3b, v47
	s_waitcnt lgkmcnt(0)
	v_mul_f32_e32 v56, 0x3fb8aa3b, v51
	v_mul_f32_e32 v59, 0x3fb8aa3b, v49
	v_mul_f32_e32 v60, 0x3fb8aa3b, v53
	v_mul_f32_e32 v33, 0x3fb8aa3b, v46
	v_mul_f32_e32 v54, 0x3fb8aa3b, v50
	v_mul_f32_e32 v46, 0xbfb8aa3b, v46
	v_mul_f32_e32 v50, 0xbfb8aa3b, v50
	v_mul_f32_e32 v47, 0xbfb8aa3b, v47
	v_mul_f32_e32 v51, 0xbfb8aa3b, v51
	v_mul_f32_e32 v57, 0x3fb8aa3b, v48
	v_mul_f32_e32 v58, 0x3fb8aa3b, v52
	v_mul_f32_e32 v48, 0xbfb8aa3b, v48
	v_mul_f32_e32 v52, 0xbfb8aa3b, v52
	v_mul_f32_e32 v49, 0xbfb8aa3b, v49
	v_mul_f32_e32 v53, 0xbfb8aa3b, v53
	v_exp_f32_e32 v55, v55
	v_exp_f32_e32 v56, v56
	v_exp_f32_e32 v59, v59
	v_exp_f32_e32 v60, v60
	v_exp_f32_e32 v33, v33
	v_exp_f32_e32 v54, v54
	v_exp_f32_e32 v46, v46
	v_exp_f32_e32 v50, v50
	v_exp_f32_e32 v47, v47
	v_exp_f32_e32 v51, v51
	v_exp_f32_e32 v57, v57
	v_exp_f32_e32 v58, v58
	v_exp_f32_e32 v48, v48
	v_exp_f32_e32 v52, v52
	v_exp_f32_e32 v49, v49
	v_exp_f32_e32 v53, v53
	s_waitcnt vmcnt(1)
	v_lshlrev_b32_e32 v61, 16, v34
	v_and_b32_e32 v34, 0xffff0000, v34
	v_lshlrev_b32_e32 v62, 16, v35
	v_and_b32_e32 v35, 0xffff0000, v35
	v_lshlrev_b32_e32 v63, 16, v36
	v_and_b32_e32 v36, 0xffff0000, v36
	v_lshlrev_b32_e32 v64, 16, v37
	v_and_b32_e32 v37, 0xffff0000, v37
	s_waitcnt vmcnt(0)
	v_lshlrev_b32_e32 v89, 16, v38
	v_and_b32_e32 v38, 0xffff0000, v38
	v_lshlrev_b32_e32 v90, 16, v39
	v_and_b32_e32 v39, 0xffff0000, v39
	v_lshlrev_b32_e32 v91, 16, v40
	v_and_b32_e32 v40, 0xffff0000, v40
	v_lshlrev_b32_e32 v92, 16, v41
	v_and_b32_e32 v41, 0xffff0000, v41
	v_mul_f32_e32 v34, v55, v34
	v_mul_f32_e32 v35, v59, v35
	v_mul_f32_e32 v36, v56, v36
	v_mul_f32_e32 v37, v60, v37
	v_mul_f32_e32 v33, v33, v61
	v_mul_f32_e32 v55, v57, v62
	v_mul_f32_e32 v54, v54, v63
	v_mul_f32_e32 v56, v58, v64
	v_mul_f32_e32 v46, v46, v89
	v_mul_f32_e32 v47, v47, v38
	v_mul_f32_e32 v48, v48, v90
	v_mul_f32_e32 v49, v49, v39
	v_mul_f32_e32 v50, v50, v91
	v_mul_f32_e32 v51, v51, v40
	v_mul_f32_e32 v52, v52, v92
	v_mul_f32_e32 v53, v53, v41
	v_cvt_pk_bf16_f32 v38, v33, v34
	v_cvt_pk_bf16_f32 v39, v55, v35
	v_cvt_pk_bf16_f32 v40, v54, v36
	v_cvt_pk_bf16_f32 v41, v56, v37
	v_cvt_pk_bf16_f32 v34, v46, v47
	v_cvt_pk_bf16_f32 v35, v48, v49
	v_cvt_pk_bf16_f32 v36, v50, v51
	v_cvt_pk_bf16_f32 v37, v52, v53
.LBB0_2152:
	s_or_b64 exec, exec, s[38:39]
	ds_write_b128 v71, v[38:41] offset:38912
	ds_write_b128 v71, v[34:37] offset:56320
	v_cmp_gt_u32_e32 vcc, s95, v130
	v_mov_b32_e32 v33, 0
	v_mov_b32_e32 v34, 0
	v_mov_b32_e32 v35, 0
	v_mov_b32_e32 v36, 0
	v_mov_b32_e32 v37, 0
	v_mov_b32_e32 v38, 0
	v_mov_b32_e32 v39, 0
	s_and_saveexec_b64 s[38:39], vcc
	s_cbranch_execz .LBB0_2154
	v_min_u32_e32 v32, s64, v130
	v_add_u32_e32 v32, s60, v32
	v_ashrrev_i32_e32 v33, 31, v32
	v_lshlrev_b64 v[36:37], 10, v[32:33]
	v_lshl_add_u64 v[32:33], v[44:45], 0, v[36:37]
	s_waitcnt vmcnt(4)
	v_mov_b32_e32 v32, v236
	v_mov_b32_e32 v33, v237
	v_mov_b32_e32 v34, v238
	v_mov_b32_e32 v35, v239
	v_lshl_add_u64 v[36:37], v[42:43], 0, v[36:37]
	v_mov_b32_e32 v36, v244
	v_mov_b32_e32 v37, v245
	v_mov_b32_e32 v38, v246
	v_mov_b32_e32 v39, v247
	ds_read_b128 v[40:43], v164 offset:4096
	ds_read_b128 v[44:47], v164 offset:4112
	s_waitcnt lgkmcnt(1)
	v_mul_f32_e32 v50, 0x3fb8aa3b, v41
	s_waitcnt lgkmcnt(0)
	v_mul_f32_e32 v51, 0x3fb8aa3b, v45
	v_mul_f32_e32 v54, 0x3fb8aa3b, v43
	v_mul_f32_e32 v55, 0x3fb8aa3b, v47
	v_mul_f32_e32 v48, 0x3fb8aa3b, v40
	v_mul_f32_e32 v49, 0x3fb8aa3b, v44
	v_mul_f32_e32 v40, 0xbfb8aa3b, v40
	v_mul_f32_e32 v44, 0xbfb8aa3b, v44
	v_mul_f32_e32 v41, 0xbfb8aa3b, v41
	v_mul_f32_e32 v45, 0xbfb8aa3b, v45
	v_mul_f32_e32 v52, 0x3fb8aa3b, v42
	v_mul_f32_e32 v53, 0x3fb8aa3b, v46
	v_mul_f32_e32 v42, 0xbfb8aa3b, v42
	v_mul_f32_e32 v46, 0xbfb8aa3b, v46
	v_mul_f32_e32 v43, 0xbfb8aa3b, v43
	v_mul_f32_e32 v47, 0xbfb8aa3b, v47
	v_exp_f32_e32 v50, v50
	v_exp_f32_e32 v51, v51
	v_exp_f32_e32 v54, v54
	v_exp_f32_e32 v55, v55
	v_exp_f32_e32 v48, v48
	v_exp_f32_e32 v49, v49
	v_exp_f32_e32 v40, v40
	v_exp_f32_e32 v44, v44
	v_exp_f32_e32 v41, v41
	v_exp_f32_e32 v45, v45
	v_exp_f32_e32 v52, v52
	v_exp_f32_e32 v53, v53
	v_exp_f32_e32 v42, v42
	v_exp_f32_e32 v46, v46
	v_exp_f32_e32 v43, v43
	v_exp_f32_e32 v47, v47
	s_waitcnt vmcnt(1)
	v_lshlrev_b32_e32 v56, 16, v32
	v_and_b32_e32 v32, 0xffff0000, v32
	v_lshlrev_b32_e32 v57, 16, v33
	v_and_b32_e32 v33, 0xffff0000, v33
	v_lshlrev_b32_e32 v58, 16, v34
	v_and_b32_e32 v34, 0xffff0000, v34
	v_lshlrev_b32_e32 v59, 16, v35
	v_and_b32_e32 v35, 0xffff0000, v35
	s_waitcnt vmcnt(0)
	v_lshlrev_b32_e32 v60, 16, v36
	v_and_b32_e32 v36, 0xffff0000, v36
	v_lshlrev_b32_e32 v61, 16, v37
	v_and_b32_e32 v37, 0xffff0000, v37
	v_lshlrev_b32_e32 v62, 16, v38
	v_and_b32_e32 v38, 0xffff0000, v38
	v_lshlrev_b32_e32 v63, 16, v39
	v_and_b32_e32 v39, 0xffff0000, v39
	v_mul_f32_e32 v32, v50, v32
	v_mul_f32_e32 v33, v54, v33
	v_mul_f32_e32 v34, v51, v34
	v_mul_f32_e32 v35, v55, v35
	v_mul_f32_e32 v48, v48, v56
	v_mul_f32_e32 v50, v52, v57
	v_mul_f32_e32 v49, v49, v58
	v_mul_f32_e32 v51, v53, v59
	v_mul_f32_e32 v40, v40, v60
	v_mul_f32_e32 v41, v41, v36
	v_mul_f32_e32 v42, v42, v61
	v_mul_f32_e32 v43, v43, v37
	v_mul_f32_e32 v44, v44, v62
	v_mul_f32_e32 v45, v45, v38
	v_mul_f32_e32 v46, v46, v63
	v_mul_f32_e32 v47, v47, v39
	v_cvt_pk_bf16_f32 v36, v48, v32
	v_cvt_pk_bf16_f32 v37, v50, v33
	v_cvt_pk_bf16_f32 v38, v49, v34
	v_cvt_pk_bf16_f32 v39, v51, v35
	v_cvt_pk_bf16_f32 v32, v40, v41
	v_cvt_pk_bf16_f32 v33, v42, v43
	v_cvt_pk_bf16_f32 v34, v44, v45
	v_cvt_pk_bf16_f32 v35, v46, v47

; __device__ __forceinline__ void gla_g3(const Params& P, unsigned char* lds) {
;     ...
;         for (int p = 0; p < 2; ++p) { const int idx = tid + p * NT, t = idx >> 4, c8 = (idx & 15) * 8; u32x4 qo = (u32x4){0u, 0u, 0u, 0u}, ko = (u32x4){0u, 0u, 0u, 0u};
;             const int tcl = t < I.L ? t : I.L - 1; const u32x4 qw = *(const u32x4*)(qg + (size_t)(I.row0 + tcl) * KEYD + I.h * DK + c8), kw = *(const u32x4*)(kg + (size_t)(I.row0 + tcl) * KEYD + I.h * DK + c8);
;     ...
;                 for (int nt = 0; nt < 2; ++nt) { const int tc = t8 < I.L ? t8 : 0; vf[nt] = *(const bf16x8*)(vT + (size_t)(I.h * DV + 32 * wid + 16 * nt + fr) * MPAD + I.row0 + tc); if (t8 >= I.L) vf[nt] = (bf16x8){0, 0, 0, 0, 0, 0, 0, 0}; }
.Lg3_loadb:
	s_and_b32 s49, s46, 3
	s_lshl_b32 s46, s49, 8
	s_lshl_b32 s98, s49, 9
	s_add_u32 s100, s54, 0x308dc00
	s_addc_u32 s101, s55, 0
	v_lshrrev_b32_e32 v48, 3, v210
	v_add_u32_e32 v48, s60, v48
	v_lshlrev_b32_e32 v48, 11, v48
	v_and_b32_e32 v49, 7, v210
	v_lshl_add_u32 v49, v49, 6, s98
	v_add_u32_e32 v48, v48, v49
	v_lshlrev_b32_e32 v49, 6, v210
	v_add_u32_e32 v49, 0x1000, v49
	s_add_i32 s98, s95, -1
	v_min_u32_e32 v220, s98, v102
	v_add_u32_e32 v220, s60, v220
	v_lshlrev_b32_e32 v220, 10, v220
	v_add_u32_e32 v220, s46, v220
	v_add_co_u32_e32 v222, vcc, v66, v220
	v_addc_co_u32_e32 v223, vcc, 0, v67, vcc
	global_load_dwordx4 v[228:231], v[222:223], off
	v_add_co_u32_e32 v224, vcc, v68, v220
	v_addc_co_u32_e32 v225, vcc, 0, v69, vcc
	global_load_dwordx4 v[232:235], v[224:225], off
	v_min_u32_e32 v220, s98, v130
	v_add_u32_e32 v220, s60, v220
	v_lshlrev_b32_e32 v220, 10, v220
	v_add_u32_e32 v220, s46, v220
	v_add_co_u32_e32 v222, vcc, v66, v220
	v_addc_co_u32_e32 v223, vcc, 0, v67, vcc
	global_load_dwordx4 v[236:239], v[222:223], off
	v_add_co_u32_e32 v224, vcc, v68, v220
	v_addc_co_u32_e32 v225, vcc, 0, v69, vcc
	global_load_dwordx4 v[244:247], v[224:225], off
	v_lshlrev_b32_e64 v220, 1, s60
	v_add_u32_e32 v223, s46, v128
	v_mul_u32_u24_e32 v223, 0x8280, v223
	v_cmp_gt_u32_e32 vcc, s95, v70
	s_nop 1
	v_cndmask_b32_e32 v222, 0, v70, vcc
	v_lshl_add_u32 v222, v222, 1, v220
	v_add_u32_e32 v222, v222, v223
	v_mov_b32_e32 v225, s78
	v_add_co_u32_e32 v224, vcc, s3, v222
	v_addc_co_u32_e32 v225, vcc, 0, v225, vcc
	global_load_dwordx4 v[194:197], v[224:225], off
	v_add_co_u32_e32 v226, vcc, 0x82800, v224
	v_addc_co_u32_e32 v227, vcc, 0, v225, vcc
	global_load_dwordx4 v[198:201], v[226:227], off
	v_cmp_gt_u32_e32 vcc, s95, v135
	s_nop 1
	v_cndmask_b32_e32 v222, 0, v135, vcc
	v_lshl_add_u32 v222, v222, 1, v220
	v_add_u32_e32 v222, v222, v223
	v_mov_b32_e32 v225, s78
	v_add_co_u32_e32 v224, vcc, s3, v222
	v_addc_co_u32_e32 v225, vcc, 0, v225, vcc
	global_load_dwordx4 v[202:205], v[224:225], off
	v_add_co_u32_e32 v226, vcc, 0x82800, v224
	v_addc_co_u32_e32 v227, vcc, 0, v225, vcc
	global_load_dwordx4 v[206:209], v[226:227], off
	s_mov_b64 s[98:99], exec
	s_cmp_eq_u32 s95, 64
	s_cbranch_scc1 .Lg3_ball
	v_cmp_gt_u32_e32 vcc, 0x80, v210
	s_nop 1
	s_and_b64 exec, exec, vcc
	s_cbranch_execz .Lg3_bskip
